# diff step: s_setprio 1 from the step barrier to the end of the softmax front, 0 during the PV tail (the lagging wave of a SIMD pair catches up), on top of v69
# baseline (speedup 1.0000x reference)
; DI void diff_item(const Params& P, char* lds, int layer, int pair, int qt, int& tab_head) {
;     ...
;     const unsigned lds0 = (unsigned)(uintptr_t)lds;
;     int goff[2];
; #pragma unroll
;     for (int i = 0; i < 2; ++i) goff[i] = (8 * w + 4 * i + (lane >> 4)) * PO + (((lane & 15) ^ (((lane >> 4) << 2) | ((2 * w + i) & 3))) * 8);
;     const u16* kg = base + head * 128 + OFF_CK;
;     const u16* vg = base + head * 128 + OFF_CV;
;     auto issue = [&](int kt, int buf) {
;         const size_t to = (size_t)(64 * kt) * PO;
; #pragma unroll
;         for (int i = 0; i < 2; ++i) {
;             glds16(kg + to + goff[i], (unsigned)__builtin_amdgcn_readfirstlane(lds0 + buf * 32768 + (2 * w + i) * 1024));
;             glds16(vg + to + goff[i], (unsigned)__builtin_amdgcn_readfirstlane(lds0 + buf * 32768 + 16384 + (2 * w + i) * 1024));
;         }
;     };
;     issue(0, 0);
;     bf16x8 qf[4];
; #pragma unroll
;     for (int s = 0; s < 4; ++s) qf[s] = *(const bf16x8*)(base + (size_t)qpos * PO + OFF_CQ + head * 128 + mp * 64 + 16 * s + 8 * hh);
;     float m = -1e30f, l = 0.f;
;     f32x16 O[4];
; #pragma unroll
;     for (int dt = 0; dt < 4; ++dt)
; #pragma unroll
;         for (int i = 0; i < 16; ++i) O[dt][i] = 0.f;
;     const int sig_r = ((r & 3) << 2) | ((r >> 2) & 3);
;     const int kx0 = (8 * mp + hh) ^ sig_r;
;     const int i16 = lane & 15, q = i16 >> 2, pp = i16 & 3, blk = (lane >> 4) & 1;
;     const int vl0 = (4 * hh + q) * 256 + (16 * ((q << 2) | (blk << 1) | ((pp >> 1) ^ hh)) + 8 * (pp & 1));
;     const int nkt = 2 * qt + 2;
.LBB0_250:
	s_or_b64 exec, exec, s[0:1]
	v_ashrrev_i32_e32 v169, 6, v168
	v_mov_b64_e32 v[2:3], s[20:21]
	s_waitcnt vmcnt(0)
	flat_load_dword v198, v[2:3]
	v_bfe_u32 v2, v168, 4, 2
	v_lshlrev_b32_e32 v7, 1, v169
	v_lshl_or_b32 v3, v169, 3, v2
	v_lshlrev_b32_e32 v2, 2, v2
	v_and_b32_e32 v7, 2, v7
	v_and_b32_e32 v6, 15, v168
	v_or_b32_e32 v9, v7, v2
	v_mul_lo_u32 v3, v3, s67
	v_bitop3_b32 v2, v7, v6, v2 bitop3:0x36
	v_bitop3_b32 v6, v9, v6, 1 bitop3:0x36
	v_lshl_or_b32 v2, v2, 3, v3
	v_lshlrev_b32_e32 v6, 3, v6
	s_sub_i32 s22, 63, s25
	v_add3_u32 v6, v3, v6, s43
	v_ashrrev_i32_e32 v3, 31, v2
	v_lshlrev_b64 v[170:171], 1, v[2:3]
	v_lshlrev_b32_e32 v9, 11, v169
	s_cmp_lg_u32 0, -1
	v_lshl_add_u64 v[2:3], s[96:97], 0, v[170:171]
	v_readfirstlane_b32 s0, v9
	s_cselect_b32 s23, 0, 0
	v_ashrrev_i32_e32 v7, 31, v6
	v_and_b32_e32 v194, 3, v169
	s_add_i32 s1, s0, s23
	s_mov_b32 s16, m0
	s_mov_b32 m0, s1
	s_nop 0
	global_load_lds_dwordx4 v[2:3], off
	s_mov_b32 m0, s16
	v_lshl_add_u64 v[2:3], s[14:15], 0, v[170:171]
	s_add_i32 s40, s23, 0x4000
	v_lshlrev_b64 v[172:173], 1, v[6:7]
	v_lshlrev_b32_e32 v5, 5, v194
	s_add_i32 s1, s0, s40
	s_mov_b32 s16, m0
	s_mov_b32 m0, s1
	s_nop 0
	global_load_lds_dwordx4 v[2:3], off
	s_mov_b32 m0, s16
	v_lshl_add_u64 v[2:3], s[96:97], 0, v[172:173]
	s_add_i32 s41, s23, 0x400
	v_and_b32_e32 v195, 31, v168
	v_lshl_or_b32 v8, s22, 7, v5
	s_add_i32 s1, s0, s41
	s_mov_b32 s16, m0
	s_mov_b32 m0, s1
	s_nop 0
	global_load_lds_dwordx4 v[2:3], off
	s_mov_b32 m0, s16
	v_lshl_add_u64 v[2:3], s[14:15], 0, v[172:173]
	s_add_i32 s51, s23, 0x4400
	v_or_b32_e32 v0, v8, v195
	s_add_i32 s0, s0, s51
	s_mov_b32 s1, m0
	s_mov_b32 m0, s0
	s_nop 0
	global_load_lds_dwordx4 v[2:3], off
	s_mov_b32 m0, s1
	v_mov_b64_e32 v[2:3], s[58:59]
	v_mad_u64_u32 v[166:167], s[0:1], v0, s52, v[2:3]
	s_lshl_b32 s16, s24, 1
	v_ashrrev_i32_e32 v197, 8, v168
	v_lshl_add_u64 v[2:3], v[166:167], 0, s[16:17]
	s_mov_b64 s[0:1], 0x1b00
	v_lshl_add_u64 v[164:165], v[2:3], 0, s[0:1]
	v_lshlrev_b32_e32 v2, 6, v197
	v_bfe_u32 v196, v168, 5, 1
	v_ashrrev_i32_e32 v3, 31, v2
	v_lshl_add_u64 v[2:3], v[2:3], 1, v[164:165]
	v_lshlrev_b32_e32 v0, 4, v196
	v_lshl_add_u64 v[2:3], v[2:3], 0, v[0:1]
	flat_load_dwordx4 v[144:147], v[2:3]
	flat_load_dwordx4 v[148:151], v[2:3] offset:32
	flat_load_dwordx4 v[152:155], v[2:3] offset:64
	flat_load_dwordx4 v[156:159], v[2:3] offset:96
	v_bfe_u32 v2, v168, 2, 2
	v_and_or_b32 v3, v4, 12, v2
	v_lshlrev_b32_e32 v4, 3, v197
	v_lshlrev_b32_e32 v193, 2, v196
	v_lshrrev_b32_e32 v6, 3, v168
	v_lshrrev_b32_e32 v7, 1, v168
	v_bitop3_b32 v3, v4, v3, v196 bitop3:0x36
	v_or_b32_e32 v4, v193, v2
	v_lshlrev_b32_e32 v2, 2, v2
	v_and_b32_e32 v6, 2, v6
	v_bitop3_b32 v7, v7, v196, 1 bitop3:0x6c
	v_or3_b32 v2, v2, v6, v7
	v_lshlrev_b32_e32 v6, 3, v168
	v_and_b32_e32 v6, 8, v6
	v_lshlrev_b32_e32 v4, 8, v4
	v_lshl_or_b32 v2, v2, 4, v6
	s_movk_i32 s0, 0x60
	v_bitop3_b32 v212, v2, s0, v4 bitop3:0x36
	s_movk_i32 s0, 0x80
	v_bitop3_b32 v213, v2, s0, v4 bitop3:0x36
	s_movk_i32 s0, 0xa0
	v_bitop3_b32 v214, v2, s0, v4 bitop3:0x36
	s_movk_i32 s0, 0xc0
	v_bitop3_b32 v215, v2, s0, v4 bitop3:0x36
	s_movk_i32 s0, 0xe0
	v_bitop3_b32 v216, v2, s0, v4 bitop3:0x36
	s_lshl_b32 s0, s25, 7
	v_or_b32_e32 v199, v2, v4
	v_bitop3_b32 v210, v2, 32, v4 bitop3:0x36
	v_bitop3_b32 v211, v2, 64, v4 bitop3:0x36
	v_subrev_u32_e32 v2, s0, v5
	v_add_u32_e32 v217, 0x1f41, v2
	v_lshlrev_b32_e32 v2, 2, v195
	v_lshl_or_b32 v2, v194, 7, v2
	v_sub_u32_e32 v0, v2, v0
	s_lshl_b32 s0, s25, 9
	s_lshl_b32 s49, s22, 1
	v_lshlrev_b32_e32 v6, 8, v168
	v_subrev_u32_e32 v0, s0, v0
	s_add_i32 s0, 0, 0x27e14
	v_mov_b32_e32 v14, v1
	v_mov_b32_e32 v15, v1
	s_add_i32 s49, s49, 2
	v_or_b32_e32 v200, 31, v8
	v_and_b32_e32 v201, 0x1f00, v6
	v_lshlrev_b32_e32 v202, 4, v3
	v_add_u32_e32 v206, s23, v9
	v_add_u32_e32 v207, s40, v9
	v_add_u32_e32 v208, s41, v9
	v_add_u32_e32 v209, s51, v9
	v_add_u32_e32 v218, s0, v0
	v_mov_b32_e32 v0, v1
	v_mov_b32_e32 v2, v1
	v_mov_b32_e32 v3, v1
	v_mov_b32_e32 v4, v1
	v_mov_b32_e32 v5, v1
	v_mov_b32_e32 v6, v1
	v_mov_b32_e32 v7, v1
	v_mov_b32_e32 v8, v1
	v_mov_b32_e32 v9, v1
	v_mov_b32_e32 v10, v1
	v_mov_b32_e32 v11, v1
	v_mov_b32_e32 v12, v1
	v_mov_b32_e32 v13, v1
	v_mov_b64_e32 v[30:31], v[14:15]
	v_mov_b64_e32 v[46:47], v[14:15]
	v_mov_b64_e32 v[62:63], v[14:15]
	v_mov_b64_e32 v[78:79], v[14:15]
	v_xor_b32_e32 v203, 32, v202
	s_mov_b32 s50, 64
	v_xor_b32_e32 v204, 64, v202
	v_xor_b32_e32 v205, 0x60, v202
	s_max_u32 s51, s49, 1
	v_mov_b32_e32 v219, 0
	v_mov_b32_e32 v226, 0xf149f2ca
	s_mov_b32 s25, 0x8000
	v_mov_b32_e32 v220, 0
	s_mov_b64 s[0:1], 0
	v_mov_b64_e32 v[28:29], v[12:13]
	v_mov_b64_e32 v[26:27], v[10:11]
	v_mov_b64_e32 v[24:25], v[8:9]
	v_mov_b64_e32 v[22:23], v[6:7]
	v_mov_b64_e32 v[20:21], v[4:5]
	v_mov_b64_e32 v[18:19], v[2:3]
	v_mov_b64_e32 v[16:17], v[0:1]
	v_mov_b64_e32 v[44:45], v[12:13]
	v_mov_b64_e32 v[42:43], v[10:11]
	v_mov_b64_e32 v[40:41], v[8:9]
	v_mov_b64_e32 v[38:39], v[6:7]
	v_mov_b64_e32 v[36:37], v[4:5]
	v_mov_b64_e32 v[34:35], v[2:3]
	v_mov_b64_e32 v[32:33], v[0:1]
	v_mov_b64_e32 v[60:61], v[12:13]
	v_mov_b64_e32 v[58:59], v[10:11]
	v_mov_b64_e32 v[56:57], v[8:9]
	v_mov_b64_e32 v[54:55], v[6:7]
	v_mov_b64_e32 v[52:53], v[4:5]
	v_mov_b64_e32 v[50:51], v[2:3]
	v_mov_b64_e32 v[48:49], v[0:1]
	v_mov_b64_e32 v[76:77], v[12:13]
	v_mov_b64_e32 v[74:75], v[10:11]
	v_mov_b64_e32 v[72:73], v[8:9]
	v_mov_b64_e32 v[70:71], v[6:7]
	v_mov_b64_e32 v[68:69], v[4:5]
	v_mov_b64_e32 v[66:67], v[2:3]
	v_mov_b64_e32 v[64:65], v[0:1]
	v_readfirstlane_b32 s63, v206
	s_add_u32 s64, s96, 0xe0000
	s_addc_u32 s65, s97, 0
	s_add_u32 s70, s14, 0xe0000
	s_addc_u32 s71, s15, 0
	s_mov_b32 s73, m0
	v_readfirstlane_b32 s100, v174
	s_nop 3
	s_and_b32 s100, s100, 0x100
	v_add_u32_e32 v14, v201, v202
	v_add_u32_e32 v15, v201, v203
	v_add_u32_e32 v221, v201, v204
	v_add_u32_e32 v222, v201, v205
	s_branch .Ldu_A
; #define LAS __attribute__((address_space(3)))
; #define MFMA(a, b, c) __builtin_amdgcn_mfma_f32_32x32x16_bf16((a), (b), (c), 0, 0, 0)
; template <typename F>
; DI void diff_step(lptr sK, lptr sV, int kx0, int vl0, const bf16x8 (&qf)[4], float& m, float& l, f32x16 (&O)[4],
;                   const LAS float* tb, bool far, float cfar, int lane, F&& mid) {
;     ...
;     lptr kr = sK + r * 256;
;     bf16x8 kf[8];
; #pragma unroll
;     for (int s = 0; s < 4; ++s) {
;         const int co = (kx0 ^ (2 * s)) * 16;
;         kf[2 * s] = *(const LAS bf16x8*)(kr + co);
;         kf[2 * s + 1] = *(const LAS bf16x8*)(kr + 8192 + co);
;     }
;     __builtin_amdgcn_sched_barrier(0);
;     mid();
;     __builtin_amdgcn_sched_barrier(0);
; #pragma unroll
;     for (int s = 0; s < 4; ++s) { p0 = MFMA(kf[2 * s], qf[s], p0); p1 = MFMA(kf[2 * s + 1], qf[s], p1); }
;     ...
;     ATTN_TAIL(4, VADDR_SWZ)
.Ldu_A:
	s_waitcnt vmcnt(0)
	s_waitcnt lgkmcnt(0)
	s_barrier
	s_setprio 1
	ds_read_b128 v[80:83], v14
	ds_read_b128 v[84:87], v14 offset:8192
	ds_read_b128 v[120:123], v15
	ds_read_b128 v[6:9], v15 offset:8192
	ds_read_b128 v[116:119], v221
	ds_read_b128 v[2:5], v221 offset:8192
	ds_read_b128 v[10:13], v222
	ds_read_b128 v[112:115], v222 offset:8192
	v_add_u32_e32 v220, 1, v220
	s_add_u32 s72, s63, 0x8000
	s_mov_b32 m0, s72
	s_nop 0
	global_load_lds_dwordx4 v170, s[64:65]
	s_add_u32 s72, s63, 0xc000
	s_mov_b32 m0, s72
	s_nop 0
	global_load_lds_dwordx4 v170, s[70:71]
	s_add_u32 s72, s63, 0x8400
	s_mov_b32 m0, s72
	s_nop 0
	global_load_lds_dwordx4 v172, s[64:65]
	s_add_u32 s72, s63, 0xc400
	s_mov_b32 m0, s72
	s_nop 0
	global_load_lds_dwordx4 v172, s[70:71]
	s_add_u32 s64, s64, 0xe0000
	s_addc_u32 s65, s65, 0
	s_add_u32 s70, s70, 0xe0000
	s_addc_u32 s71, s71, 0
	v_cmp_gt_i32_e32 vcc, s42, v217
	s_waitcnt lgkmcnt(7)
	v_mfma_f32_32x32x16_bf16 v[96:111], v[80:83], v[144:147], 0
	s_waitcnt lgkmcnt(6)
	v_mfma_f32_32x32x16_bf16 v[80:95], v[84:87], v[144:147], 0
	s_waitcnt lgkmcnt(5)
	v_mfma_f32_32x32x16_bf16 v[96:111], v[120:123], v[148:151], v[96:111]
	s_waitcnt lgkmcnt(4)
	v_mfma_f32_32x32x16_bf16 v[80:95], v[6:9], v[148:151], v[80:95]
	s_waitcnt lgkmcnt(3)
	v_mfma_f32_32x32x16_bf16 v[96:111], v[116:119], v[152:155], v[96:111]
	s_waitcnt lgkmcnt(2)
	v_mfma_f32_32x32x16_bf16 v[80:95], v[2:5], v[152:155], v[80:95]
	ds_read_b64_tr_b16 v[2:3], v199 offset:16384
	ds_read_b64_tr_b16 v[4:5], v210 offset:18432
	ds_read_b64_tr_b16 v[6:7], v211 offset:16384
	ds_read_b64_tr_b16 v[8:9], v212 offset:18432
	s_waitcnt lgkmcnt(5)
	v_mfma_f32_32x32x16_bf16 v[96:111], v[10:13], v[156:159], v[96:111]
	ds_read_b64_tr_b16 v[10:11], v213 offset:16384
	ds_read_b64_tr_b16 v[12:13], v214 offset:18432
	ds_read_b64_tr_b16 v[160:161], v215 offset:16384
	ds_read_b64_tr_b16 v[162:163], v216 offset:18432
	s_waitcnt lgkmcnt(8)
	v_mfma_f32_32x32x16_bf16 v[80:95], v[112:115], v[156:159], v[80:95]
	s_and_saveexec_b64 s[22:23], vcc
	s_xor_b64 s[22:23], exec, s[22:23]
	s_cbranch_execz .LBB0_258_a
	ds_read2_b32 v[112:113], v218 offset0:58 offset1:59
	ds_read2_b32 v[114:115], v218 offset0:56 offset1:57
	ds_read2_b32 v[116:117], v218 offset0:50 offset1:51
	ds_read2_b32 v[118:119], v218 offset0:48 offset1:49
	ds_read2_b32 v[120:121], v218 offset0:26 offset1:27
	ds_read2_b32 v[122:123], v218 offset0:24 offset1:25
	ds_read2_b32 v[124:125], v218 offset0:18 offset1:19
	ds_read2_b32 v[126:127], v218 offset0:16 offset1:17
	ds_read2_b32 v[128:129], v218 offset0:42 offset1:43
	ds_read2_b32 v[130:131], v218 offset0:40 offset1:41
	ds_read2_b32 v[132:133], v218 offset0:34 offset1:35
	ds_read2_b32 v[134:135], v218 offset0:32 offset1:33
	ds_read2_b32 v[136:137], v218 offset0:10 offset1:11
	ds_read2_b32 v[138:139], v218 offset0:8 offset1:9
	ds_read2_b32 v[140:141], v218 offset0:2 offset1:3
	ds_read2_b32 v[142:143], v218 offset1:1
	s_nop 7
	s_nop 7
	s_nop 3
	s_waitcnt lgkmcnt(14)
	v_fma_f32 v96, v96, v178, v113
	s_waitcnt lgkmcnt(11)
	v_fma_f32 v80, v80, v178, v121
	v_fma_f32 v97, v97, v178, v112
	v_fma_f32 v81, v81, v178, v120
	v_fma_f32 v98, v98, v178, v115
	s_waitcnt lgkmcnt(10)
	v_fma_f32 v82, v82, v178, v123
	v_fma_f32 v99, v99, v178, v114
	v_fma_f32 v83, v83, v178, v122
	v_max3_f32 v112, v96, v97, v80
	v_fma_f32 v100, v100, v178, v117
	v_fma_f32 v101, v101, v178, v116
	v_fma_f32 v102, v102, v178, v119
	s_nop 0
	v_max3_f32 v113, v98, v99, v81
	v_fma_f32 v103, v103, v178, v118
	v_max3_f32 v112, v112, v82, v83
	s_waitcnt lgkmcnt(9)
	v_fma_f32 v84, v84, v178, v125
	v_fma_f32 v85, v85, v178, v124
	s_waitcnt lgkmcnt(8)
	v_fma_f32 v86, v86, v178, v127
	v_fma_f32 v87, v87, v178, v126
	v_max3_f32 v113, v113, v102, v103
	v_max3_f32 v112, v112, v100, v101
	s_waitcnt lgkmcnt(7)
	v_fma_f32 v104, v104, v178, v129
	v_fma_f32 v105, v105, v178, v128
	s_waitcnt lgkmcnt(6)
	v_fma_f32 v106, v106, v178, v131
	v_fma_f32 v107, v107, v178, v130
	v_max3_f32 v113, v113, v86, v87
	v_max3_f32 v112, v112, v84, v85
	s_waitcnt lgkmcnt(3)
	v_fma_f32 v88, v88, v178, v137
	v_fma_f32 v89, v89, v178, v136
	s_waitcnt lgkmcnt(2)
	v_fma_f32 v90, v90, v178, v139
	v_fma_f32 v91, v91, v178, v138
	v_max3_f32 v113, v113, v106, v107
	v_max3_f32 v112, v112, v104, v105
	v_fma_f32 v108, v108, v178, v133
	v_fma_f32 v109, v109, v178, v132
	v_fma_f32 v110, v110, v178, v135
	v_fma_f32 v111, v111, v178, v134
	s_nop 0
	v_max3_f32 v113, v113, v90, v91
	v_max3_f32 v112, v112, v88, v89
	s_waitcnt lgkmcnt(1)
	v_fma_f32 v92, v92, v178, v141
	v_fma_f32 v93, v93, v178, v140
	s_waitcnt lgkmcnt(0)
	v_fma_f32 v94, v94, v178, v143
	v_fma_f32 v95, v95, v178, v142
	v_max3_f32 v113, v113, v110, v111
	v_max3_f32 v112, v112, v108, v109
	s_nop 0
	v_max3_f32 v112, v112, v92, v93
	v_max3_f32 v113, v113, v94, v95
	s_nop 0
	v_max_f32_e32 v113, v113, v113
	v_max_f32_e32 v112, v112, v112
	v_max_f32_e32 v112, v112, v113
	v_mov_b32_e32 v113, v112
	s_nop 1
	v_permlane32_swap_b32_e32 v112, v113
	v_max_f32_e32 v113, v113, v113
	v_max_f32_e32 v112, v112, v112
	v_max_f32_e32 v112, v112, v113
	v_sub_f32_e32 v113, v112, v226
	v_cmp_lt_f32_e32 vcc, s45, v113
	v_max_f32_e32 v112, v226, v112
	s_nop 0
	v_cndmask_b32_e32 v227, v226, v112, vcc
	v_sub_f32 v112, v96, v227
	v_sub_f32 v128, v80, v227
	v_sub_f32 v113, v97, v227
	v_sub_f32 v129, v81, v227
	v_sub_f32 v114, v98, v227
	v_sub_f32 v130, v82, v227
	v_sub_f32 v115, v99, v227
	v_sub_f32 v131, v83, v227
	v_sub_f32 v116, v100, v227
	v_sub_f32 v132, v84, v227
	v_sub_f32 v117, v101, v227
	v_sub_f32 v133, v85, v227
	v_sub_f32 v118, v102, v227
	v_sub_f32 v134, v86, v227
	v_sub_f32 v119, v103, v227
	v_sub_f32 v135, v87, v227
	v_sub_f32 v120, v104, v227
	v_sub_f32 v136, v88, v227
	v_sub_f32 v121, v105, v227
	v_sub_f32 v137, v89, v227
	v_sub_f32 v122, v106, v227
	v_sub_f32 v138, v90, v227
	v_sub_f32 v123, v107, v227
	v_sub_f32 v139, v91, v227
	v_sub_f32 v124, v108, v227
	v_sub_f32 v140, v92, v227
	v_sub_f32 v125, v109, v227
	v_sub_f32 v141, v93, v227
	v_sub_f32 v126, v110, v227
	v_sub_f32 v142, v94, v227
	v_sub_f32 v127, v111, v227
	v_sub_f32 v143, v95, v227

.Ldf_far_nofix_a:
.LBB0_260_a:
	s_or_b64 exec, exec, s[22:23]
	s_setprio 0
	v_cmp_neq_f32_e32 vcc, v227, v226
	ds_read_b64_tr_b16 v[80:81], v199 offset:20480
	ds_read_b64_tr_b16 v[82:83], v210 offset:22528
	ds_read_b64_tr_b16 v[84:85], v211 offset:20480
	ds_read_b64_tr_b16 v[86:87], v212 offset:22528
	ds_read_b64_tr_b16 v[88:89], v213 offset:20480
	ds_read_b64_tr_b16 v[90:91], v214 offset:22528
	ds_read_b64_tr_b16 v[92:93], v215 offset:20480
	ds_read_b64_tr_b16 v[94:95], v216 offset:22528
	v_exp_f32_e32 v104, v112
	v_exp_f32_e32 v105, v113
	v_exp_f32_e32 v106, v114
	v_exp_f32_e32 v107, v115
	v_exp_f32_e32 v108, v116
	v_exp_f32_e32 v109, v117
	v_exp_f32_e32 v110, v118
	v_exp_f32_e32 v111, v119
	s_cbranch_vccz .Ldf_norescale_a
	v_sub_f32_e32 v246, v226, v227
	v_exp_f32_e32 v246, v246
	s_nop 0
	v_mul_f32_e32 v219, v219, v246
	v_pk_mul_f32 v[78:79], v[78:79], v[246:247] op_sel_hi:[1,0]
	v_pk_mul_f32 v[76:77], v[76:77], v[246:247] op_sel_hi:[1,0]
	v_pk_mul_f32 v[74:75], v[74:75], v[246:247] op_sel_hi:[1,0]
	v_pk_mul_f32 v[72:73], v[72:73], v[246:247] op_sel_hi:[1,0]
	v_pk_mul_f32 v[70:71], v[70:71], v[246:247] op_sel_hi:[1,0]
	v_pk_mul_f32 v[68:69], v[68:69], v[246:247] op_sel_hi:[1,0]
	v_pk_mul_f32 v[66:67], v[66:67], v[246:247] op_sel_hi:[1,0]
	v_pk_mul_f32 v[64:65], v[64:65], v[246:247] op_sel_hi:[1,0]
	v_pk_mul_f32 v[62:63], v[62:63], v[246:247] op_sel_hi:[1,0]
	v_pk_mul_f32 v[60:61], v[60:61], v[246:247] op_sel_hi:[1,0]
	v_pk_mul_f32 v[58:59], v[58:59], v[246:247] op_sel_hi:[1,0]
	v_pk_mul_f32 v[56:57], v[56:57], v[246:247] op_sel_hi:[1,0]
	v_pk_mul_f32 v[54:55], v[54:55], v[246:247] op_sel_hi:[1,0]
	v_pk_mul_f32 v[52:53], v[52:53], v[246:247] op_sel_hi:[1,0]
	v_pk_mul_f32 v[50:51], v[50:51], v[246:247] op_sel_hi:[1,0]
	v_pk_mul_f32 v[48:49], v[48:49], v[246:247] op_sel_hi:[1,0]
	v_pk_mul_f32 v[46:47], v[46:47], v[246:247] op_sel_hi:[1,0]
	v_pk_mul_f32 v[44:45], v[44:45], v[246:247] op_sel_hi:[1,0]
	v_pk_mul_f32 v[42:43], v[42:43], v[246:247] op_sel_hi:[1,0]
	v_pk_mul_f32 v[40:41], v[40:41], v[246:247] op_sel_hi:[1,0]
	v_pk_mul_f32 v[38:39], v[38:39], v[246:247] op_sel_hi:[1,0]
	v_pk_mul_f32 v[36:37], v[36:37], v[246:247] op_sel_hi:[1,0]
	v_pk_mul_f32 v[34:35], v[34:35], v[246:247] op_sel_hi:[1,0]
	v_pk_mul_f32 v[32:33], v[32:33], v[246:247] op_sel_hi:[1,0]
	v_pk_mul_f32 v[30:31], v[30:31], v[246:247] op_sel_hi:[1,0]
	v_pk_mul_f32 v[28:29], v[28:29], v[246:247] op_sel_hi:[1,0]
	v_pk_mul_f32 v[26:27], v[26:27], v[246:247] op_sel_hi:[1,0]
	v_pk_mul_f32 v[24:25], v[24:25], v[246:247] op_sel_hi:[1,0]
	v_pk_mul_f32 v[22:23], v[22:23], v[246:247] op_sel_hi:[1,0]
	v_pk_mul_f32 v[20:21], v[20:21], v[246:247] op_sel_hi:[1,0]
	v_pk_mul_f32 v[18:19], v[18:19], v[246:247] op_sel_hi:[1,0]
	v_pk_mul_f32 v[16:17], v[16:17], v[246:247] op_sel_hi:[1,0]

; #define LAS __attribute__((address_space(3)))
; DI void diff_item(const Params& P, char* lds, int layer, int pair, int qt, int& tab_head) {
;     ...
;     auto issue = [&](int kt, int buf) {
;         const size_t to = (size_t)(64 * kt) * PO;
; #pragma unroll
;         for (int i = 0; i < 2; ++i) {
;             glds16(kg + to + goff[i], (unsigned)__builtin_amdgcn_readfirstlane(lds0 + buf * 32768 + (2 * w + i) * 1024));
;             glds16(vg + to + goff[i], (unsigned)__builtin_amdgcn_readfirstlane(lds0 + buf * 32768 + 16384 + (2 * w + i) * 1024));
;         }
;     };
;     ...
;     for (int kt = 0; kt < nkt; ++kt) {
;         asm volatile("s_waitcnt vmcnt(0)" ::: "memory");
;         __syncthreads();
;         auto mid = [&]() { if (kt + 1 < nkt) issue(kt + 1, (kt + 1) & 1); };
;         if (64 * kt <= q0 + 32 * qs + 31) {
;             const bool far = (q0 + 32 * qs) - (64 * kt + 63) >= 1536;
;             const LAS float* tb = (const LAS float*)ctab + (qpos - 64 * kt - 4 * hh + 64 - 63);
;             lptr bufp = (lptr)lds + (kt & 1) * 32768;
;             diff_step(bufp, bufp + 16384, kx0, vl0, qf, m, l, O, tb, far, cfar, lane, mid);
.Ldu_B:
	s_waitcnt vmcnt(0)
	s_sub_i32 s22, s50, 64
	v_cmp_le_u32_e32 vcc, s22, v200
	v_add_u32_e32 v0, 1, v220
	s_waitcnt lgkmcnt(0)
	s_barrier
	s_and_saveexec_b64 s[22:23], vcc
	s_xor_b64 s[40:41], exec, s[22:23]
	s_cbranch_execz .LBB0_263_b
	v_add_u32_e32 v220, 1, v220
	v_cmp_gt_u32_e32 vcc, s49, v220
	s_setprio 1
	ds_read_b128 v[80:83], v14 offset:32768
	ds_read_b128 v[84:87], v14 offset:40960
	ds_read_b128 v[120:123], v15 offset:32768
	ds_read_b128 v[6:9], v15 offset:40960
	ds_read_b128 v[116:119], v221 offset:32768
	ds_read_b128 v[2:5], v221 offset:40960
	ds_read_b128 v[10:13], v222 offset:32768
	ds_read_b128 v[112:115], v222 offset:40960
	s_and_saveexec_b64 s[22:23], vcc
	s_cbranch_execz .LBB0_256_b
	s_mov_b32 s72, s63
	s_mov_b32 m0, s72
	s_nop 0
	global_load_lds_dwordx4 v170, s[64:65]
	s_add_u32 s72, s63, 0x4000
	s_mov_b32 m0, s72
	s_nop 0
	global_load_lds_dwordx4 v170, s[70:71]
	s_add_u32 s72, s63, 0x400
	s_mov_b32 m0, s72
	s_nop 0
	global_load_lds_dwordx4 v172, s[64:65]
	s_add_u32 s72, s63, 0x4400
	s_mov_b32 m0, s72
	s_nop 0
	global_load_lds_dwordx4 v172, s[70:71]
	s_add_u32 s64, s64, 0xe0000
	s_addc_u32 s65, s65, 0
	s_add_u32 s70, s70, 0xe0000
	s_addc_u32 s71, s71, 0

.Ldf_far_nofix_b:
.LBB0_260_b:
	s_or_b64 exec, exec, s[22:23]
	s_setprio 0
	v_cmp_neq_f32_e32 vcc, v227, v226
	ds_read_b64_tr_b16 v[80:81], v199 offset:53248
	ds_read_b64_tr_b16 v[82:83], v210 offset:55296
	ds_read_b64_tr_b16 v[84:85], v211 offset:53248
	ds_read_b64_tr_b16 v[86:87], v212 offset:55296
	ds_read_b64_tr_b16 v[88:89], v213 offset:53248
	ds_read_b64_tr_b16 v[90:91], v214 offset:55296
	ds_read_b64_tr_b16 v[92:93], v215 offset:53248
	ds_read_b64_tr_b16 v[94:95], v216 offset:55296
	v_exp_f32_e32 v104, v112
	v_exp_f32_e32 v105, v113
	v_exp_f32_e32 v106, v114
	v_exp_f32_e32 v107, v115
	v_exp_f32_e32 v108, v116
	v_exp_f32_e32 v109, v117
	v_exp_f32_e32 v110, v118
	v_exp_f32_e32 v111, v119
	s_cbranch_vccz .Ldf_norescale_b
	v_sub_f32_e32 v246, v226, v227
	v_exp_f32_e32 v246, v246
	s_nop 0
	v_mul_f32_e32 v219, v219, v246
	v_pk_mul_f32 v[78:79], v[78:79], v[246:247] op_sel_hi:[1,0]
	v_pk_mul_f32 v[76:77], v[76:77], v[246:247] op_sel_hi:[1,0]
	v_pk_mul_f32 v[74:75], v[74:75], v[246:247] op_sel_hi:[1,0]
	v_pk_mul_f32 v[72:73], v[72:73], v[246:247] op_sel_hi:[1,0]
	v_pk_mul_f32 v[70:71], v[70:71], v[246:247] op_sel_hi:[1,0]
	v_pk_mul_f32 v[68:69], v[68:69], v[246:247] op_sel_hi:[1,0]
	v_pk_mul_f32 v[66:67], v[66:67], v[246:247] op_sel_hi:[1,0]
	v_pk_mul_f32 v[64:65], v[64:65], v[246:247] op_sel_hi:[1,0]
	v_pk_mul_f32 v[62:63], v[62:63], v[246:247] op_sel_hi:[1,0]
	v_pk_mul_f32 v[60:61], v[60:61], v[246:247] op_sel_hi:[1,0]
	v_pk_mul_f32 v[58:59], v[58:59], v[246:247] op_sel_hi:[1,0]
	v_pk_mul_f32 v[56:57], v[56:57], v[246:247] op_sel_hi:[1,0]
	v_pk_mul_f32 v[54:55], v[54:55], v[246:247] op_sel_hi:[1,0]
	v_pk_mul_f32 v[52:53], v[52:53], v[246:247] op_sel_hi:[1,0]
	v_pk_mul_f32 v[50:51], v[50:51], v[246:247] op_sel_hi:[1,0]
	v_pk_mul_f32 v[48:49], v[48:49], v[246:247] op_sel_hi:[1,0]
	v_pk_mul_f32 v[46:47], v[46:47], v[246:247] op_sel_hi:[1,0]
	v_pk_mul_f32 v[44:45], v[44:45], v[246:247] op_sel_hi:[1,0]
	v_pk_mul_f32 v[42:43], v[42:43], v[246:247] op_sel_hi:[1,0]
	v_pk_mul_f32 v[40:41], v[40:41], v[246:247] op_sel_hi:[1,0]
	v_pk_mul_f32 v[38:39], v[38:39], v[246:247] op_sel_hi:[1,0]
	v_pk_mul_f32 v[36:37], v[36:37], v[246:247] op_sel_hi:[1,0]
	v_pk_mul_f32 v[34:35], v[34:35], v[246:247] op_sel_hi:[1,0]
	v_pk_mul_f32 v[32:33], v[32:33], v[246:247] op_sel_hi:[1,0]
	v_pk_mul_f32 v[30:31], v[30:31], v[246:247] op_sel_hi:[1,0]
	v_pk_mul_f32 v[28:29], v[28:29], v[246:247] op_sel_hi:[1,0]
	v_pk_mul_f32 v[26:27], v[26:27], v[246:247] op_sel_hi:[1,0]
	v_pk_mul_f32 v[24:25], v[24:25], v[246:247] op_sel_hi:[1,0]
	v_pk_mul_f32 v[22:23], v[22:23], v[246:247] op_sel_hi:[1,0]
	v_pk_mul_f32 v[20:21], v[20:21], v[246:247] op_sel_hi:[1,0]
	v_pk_mul_f32 v[18:19], v[18:19], v[246:247] op_sel_hi:[1,0]
	v_pk_mul_f32 v[16:17], v[16:17], v[246:247] op_sel_hi:[1,0]

; DI void diff_item(const Params& P, char* lds, int layer, int pair, int qt, int& tab_head) {
;     ...
;     __syncthreads();
;     const float inv = 1.f / xhalf_sum(l);
;     float* cmb = (float*)lds;
;     if (mp == 1) {
; #pragma unroll
;         for (int dt = 0; dt < 4; ++dt)
; #pragma unroll
;             for (int i = 0; i < 16; ++i) cmb[(qs * 128 + 32 * dt + (i & 3) + 8 * (i >> 2) + 4 * hh) * 32 + r] = O[dt][i] * inv;
;     }
.LBB0_266:
	s_or_b64 exec, exec, s[0:1]
	s_setprio 0
	s_mov_b32 m0, s73
	v_mov_b32_e32 v0, v219
	s_nop 1
	v_permlane32_swap_b32_e32 v219, v0
	v_add_f32_e32 v0, v219, v0
	v_div_scale_f32 v2, s[0:1], v0, v0, 1.0
	v_rcp_f32_e32 v3, v2
	s_barrier
	v_fma_f32 v4, -v2, v3, 1.0
	v_fmac_f32_e32 v3, v4, v3
	v_div_scale_f32 v4, vcc, 1.0, v0, 1.0
	v_mul_f32_e32 v5, v4, v3
	v_fma_f32 v6, -v2, v5, v4
	v_fmac_f32_e32 v5, v6, v3
	v_fma_f32 v2, -v2, v5, v4
	v_div_fmas_f32 v2, v2, v3, v5
	v_div_fixup_f32 v8, v2, v0, 1.0
	v_cmp_eq_u32_e32 vcc, 1, v197
	v_lshlrev_b32_e32 v2, 9, v196
	v_lshl_add_u32 v3, v195, 2, 0
	s_and_saveexec_b64 s[0:1], vcc
	s_cbranch_execz .LBB0_268
	v_lshlrev_b32_e32 v4, 14, v194
	v_mul_f32_e32 v0, v64, v8
	v_add3_u32 v4, v3, v4, v2
	v_mul_f32_e32 v5, v65, v8
	ds_write2_b32 v4, v0, v5 offset1:32
	v_mul_f32_e32 v0, v66, v8
	v_mul_f32_e32 v5, v67, v8
	ds_write2_b32 v4, v0, v5 offset0:64 offset1:96
	v_mul_f32_e32 v0, v68, v8
	v_mul_f32_e32 v5, v69, v8
	v_add_u32_e32 v6, 0x400, v4
	ds_write2_b32 v6, v0, v5 offset1:32
	v_mul_f32_e32 v0, v70, v8
	v_mul_f32_e32 v5, v71, v8
	ds_write2_b32 v6, v0, v5 offset0:64 offset1:96
	v_mul_f32_e32 v0, v72, v8
	v_mul_f32_e32 v5, v73, v8
	v_add_u32_e32 v6, 0x800, v4
	ds_write2_b32 v6, v0, v5 offset1:32
	v_mul_f32_e32 v0, v74, v8
	v_mul_f32_e32 v5, v75, v8
	ds_write2_b32 v6, v0, v5 offset0:64 offset1:96
	v_mul_f32_e32 v0, v76, v8
	v_mul_f32_e32 v5, v77, v8
	v_add_u32_e32 v6, 0xc00, v4
	ds_write2_b32 v6, v0, v5 offset1:32
	v_mul_f32_e32 v0, v78, v8
	v_mul_f32_e32 v5, v79, v8
	ds_write2_b32 v6, v0, v5 offset0:64 offset1:96
	v_mul_f32_e32 v0, v48, v8
	v_mul_f32_e32 v5, v49, v8
	v_add_u32_e32 v6, 0x1000, v4
	ds_write2_b32 v6, v0, v5 offset1:32
	v_mul_f32_e32 v0, v50, v8
	v_mul_f32_e32 v5, v51, v8
	ds_write2_b32 v6, v0, v5 offset0:64 offset1:96
	v_mul_f32_e32 v0, v52, v8
	v_mul_f32_e32 v5, v53, v8
	v_add_u32_e32 v6, 0x1400, v4
	ds_write2_b32 v6, v0, v5 offset1:32
	v_mul_f32_e32 v0, v54, v8
	v_mul_f32_e32 v5, v55, v8
	ds_write2_b32 v6, v0, v5 offset0:64 offset1:96
	v_mul_f32_e32 v0, v56, v8
	v_mul_f32_e32 v5, v57, v8
	v_add_u32_e32 v6, 0x1800, v4
	ds_write2_b32 v6, v0, v5 offset1:32
	v_mul_f32_e32 v0, v58, v8
	v_mul_f32_e32 v5, v59, v8
	ds_write2_b32 v6, v0, v5 offset0:64 offset1:96
	v_mul_f32_e32 v0, v60, v8
	v_mul_f32_e32 v5, v61, v8
	v_add_u32_e32 v6, 0x1c00, v4
	ds_write2_b32 v6, v0, v5 offset1:32
	v_mul_f32_e32 v0, v62, v8
	v_mul_f32_e32 v5, v63, v8
	ds_write2_b32 v6, v0, v5 offset0:64 offset1:96
	v_mul_f32_e32 v0, v32, v8
	v_mul_f32_e32 v5, v33, v8
	v_add_u32_e32 v6, 0x2000, v4
	ds_write2_b32 v6, v0, v5 offset1:32
	v_mul_f32_e32 v0, v34, v8
	v_mul_f32_e32 v5, v35, v8
	ds_write2_b32 v6, v0, v5 offset0:64 offset1:96
	v_mul_f32_e32 v0, v36, v8
	v_mul_f32_e32 v5, v37, v8
	v_add_u32_e32 v6, 0x2400, v4
	ds_write2_b32 v6, v0, v5 offset1:32
	v_mul_f32_e32 v0, v38, v8
	v_mul_f32_e32 v5, v39, v8
	ds_write2_b32 v6, v0, v5 offset0:64 offset1:96
	v_mul_f32_e32 v0, v40, v8
	v_mul_f32_e32 v5, v41, v8
	v_add_u32_e32 v6, 0x2800, v4
	ds_write2_b32 v6, v0, v5 offset1:32
	v_mul_f32_e32 v0, v42, v8
	v_mul_f32_e32 v5, v43, v8
	ds_write2_b32 v6, v0, v5 offset0:64 offset1:96
	v_mul_f32_e32 v0, v44, v8
	v_mul_f32_e32 v5, v45, v8
	v_add_u32_e32 v6, 0x2c00, v4
	ds_write2_b32 v6, v0, v5 offset1:32
	v_mul_f32_e32 v0, v46, v8
	v_mul_f32_e32 v5, v47, v8
	ds_write2_b32 v6, v0, v5 offset0:64 offset1:96
	v_mul_f32_e32 v0, v16, v8
	v_mul_f32_e32 v5, v17, v8
	v_add_u32_e32 v6, 0x3000, v4
	ds_write2_b32 v6, v0, v5 offset1:32
	v_mul_f32_e32 v0, v18, v8
	v_mul_f32_e32 v5, v19, v8
	ds_write2_b32 v6, v0, v5 offset0:64 offset1:96
	v_mul_f32_e32 v0, v20, v8
	v_mul_f32_e32 v5, v21, v8
	v_add_u32_e32 v6, 0x3400, v4
	ds_write2_b32 v6, v0, v5 offset1:32
	v_mul_f32_e32 v0, v22, v8
	v_mul_f32_e32 v5, v23, v8
	ds_write2_b32 v6, v0, v5 offset0:64 offset1:96
	v_mul_f32_e32 v0, v24, v8
	v_mul_f32_e32 v5, v25, v8
	v_add_u32_e32 v6, 0x3800, v4
	ds_write2_b32 v6, v0, v5 offset1:32
	v_mul_f32_e32 v0, v26, v8
	v_mul_f32_e32 v5, v27, v8
	ds_write2_b32 v6, v0, v5 offset0:64 offset1:96
	v_mul_f32_e32 v0, v28, v8
	v_mul_f32_e32 v5, v29, v8
	v_add_u32_e32 v4, 0x3c00, v4
	ds_write2_b32 v4, v0, v5 offset1:32
	v_mul_f32_e32 v0, v30, v8
	v_mul_f32_e32 v5, v31, v8
	ds_write2_b32 v4, v0, v5 offset0:64 offset1:96
